# prologue de-serialisation: kernel-argument pointer table fetched with wide scalar loads in one batch
# baseline (speedup 1.0000x reference)
; __global__ void __launch_bounds__(NWAVES * 64, 2) mk_fwd(Args a) {
;     ...
;     if (tid0 == 0) {
; #pragma unroll
;         for (int i = 0; i < 27; ++i) LP[i] = (unsigned long long)a.in[i];
;         LP[27] = (unsigned long long)a.out; LP[28] = (unsigned long long)a.ws;
;     }
.LBB0_3:
	s_or_b64 exec, exec, s[2:3]
	v_cmp_eq_u32_e32 vcc, 0, v0
	v_cmp_ne_u32_e64 s[4:5], 0, v0
	s_waitcnt lgkmcnt(0)
	s_barrier
	s_and_saveexec_b64 s[2:3], s[4:5]
	s_xor_b64 s[2:3], exec, s[2:3]
	s_load_dwordx2 s[6:7], s[0:1], 0xe0
	s_or_saveexec_b64 s[2:3], s[2:3]
	s_waitcnt lgkmcnt(0)
	v_mov_b64_e32 v[2:3], s[6:7]
	s_xor_b64 exec, exec, s[2:3]
	s_cbranch_execz .LBB0_7
	s_load_dwordx8 s[12:19], s[0:1], 0x0
	s_add_i32 s4, 0, 0x22100
	s_load_dwordx8 s[20:27], s[0:1], 0x20
	s_load_dwordx16 s[32:47], s[0:1], 0x40
	s_load_dwordx16 s[48:63], s[0:1], 0x80
	s_load_dwordx8 s[64:71], s[0:1], 0xc0
	s_load_dwordx2 s[72:73], s[0:1], 0xe0
	s_add_i32 s5, 0, 0x22108
	v_mov_b32_e32 v1, s4
	s_waitcnt lgkmcnt(0)
	v_mov_b64_e32 v[2:3], s[12:13]
	ds_write_b64 v1, v[2:3]
	v_mov_b32_e32 v1, s5
	v_mov_b64_e32 v[2:3], s[14:15]
	s_add_i32 s4, 0, 0x22110
	ds_write_b64 v1, v[2:3]
	v_mov_b32_e32 v1, s4
	v_mov_b64_e32 v[2:3], s[16:17]
	s_add_i32 s4, 0, 0x22118
	ds_write_b64 v1, v[2:3]
	v_mov_b32_e32 v1, s4
	v_mov_b64_e32 v[2:3], s[18:19]
	s_add_i32 s4, 0, 0x22120
	ds_write_b64 v1, v[2:3]
	v_mov_b32_e32 v1, s4
	v_mov_b64_e32 v[2:3], s[20:21]
	s_add_i32 s4, 0, 0x22128
	ds_write_b64 v1, v[2:3]
	v_mov_b32_e32 v1, s4
	v_mov_b64_e32 v[2:3], s[22:23]
	s_add_i32 s4, 0, 0x22130
	ds_write_b64 v1, v[2:3]
	v_mov_b32_e32 v1, s4
	v_mov_b64_e32 v[2:3], s[24:25]
	s_add_i32 s4, 0, 0x22138
	ds_write_b64 v1, v[2:3]
	v_mov_b32_e32 v1, s4
	v_mov_b64_e32 v[2:3], s[26:27]
	ds_write_b64 v1, v[2:3]
	v_mov_b32_e32 v1, 0x22140
	v_mov_b64_e32 v[2:3], s[32:33]
	ds_write_b64 v1, v[2:3]
	v_mov_b32_e32 v1, 0x22148
	v_mov_b64_e32 v[2:3], s[34:35]
	ds_write_b64 v1, v[2:3]
	v_mov_b32_e32 v1, 0x22150
	v_mov_b64_e32 v[2:3], s[36:37]
	ds_write_b64 v1, v[2:3]
	v_mov_b32_e32 v1, 0x22158
	v_mov_b64_e32 v[2:3], s[38:39]
	ds_write_b64 v1, v[2:3]
	v_mov_b32_e32 v1, 0x22160
	v_mov_b64_e32 v[2:3], s[40:41]
	ds_write_b64 v1, v[2:3]
	v_mov_b32_e32 v1, 0x22168
	v_mov_b64_e32 v[2:3], s[42:43]
	ds_write_b64 v1, v[2:3]
	v_mov_b32_e32 v1, 0x22170
	v_mov_b64_e32 v[2:3], s[44:45]
	ds_write_b64 v1, v[2:3]
	v_mov_b32_e32 v1, 0x22178
	v_mov_b64_e32 v[2:3], s[46:47]
	ds_write_b64 v1, v[2:3]
	v_mov_b32_e32 v1, 0x22180
	v_mov_b64_e32 v[2:3], s[48:49]
	ds_write_b64 v1, v[2:3]
	v_mov_b32_e32 v1, 0x22188
	v_mov_b64_e32 v[2:3], s[50:51]
	ds_write_b64 v1, v[2:3]
	v_mov_b32_e32 v1, 0x22190
	v_mov_b64_e32 v[2:3], s[52:53]
	ds_write_b64 v1, v[2:3]
	v_mov_b32_e32 v1, 0x22198
	v_mov_b64_e32 v[2:3], s[54:55]
	ds_write_b64 v1, v[2:3]
	v_mov_b32_e32 v1, 0x221a0
	v_mov_b64_e32 v[2:3], s[56:57]
	ds_write_b64 v1, v[2:3]
	v_mov_b32_e32 v1, 0x221a8
	v_mov_b64_e32 v[2:3], s[58:59]
	ds_write_b64 v1, v[2:3]
	v_mov_b32_e32 v1, 0x221b0
	v_mov_b64_e32 v[2:3], s[60:61]
	ds_write_b64 v1, v[2:3]
	v_mov_b32_e32 v1, 0x221b8
	v_mov_b64_e32 v[2:3], s[62:63]
	ds_write_b64 v1, v[2:3]
	v_mov_b32_e32 v1, 0x221c0
	v_mov_b64_e32 v[2:3], s[64:65]
	ds_write_b64 v1, v[2:3]
	v_mov_b32_e32 v1, 0x221c8
	v_mov_b64_e32 v[2:3], s[66:67]
	ds_write_b64 v1, v[2:3]
	v_mov_b32_e32 v1, 0x221d0
	v_mov_b64_e32 v[2:3], s[68:69]
	ds_write_b64 v1, v[2:3]
	v_mov_b32_e32 v1, 0x221d8
	v_mov_b64_e32 v[2:3], s[70:71]
	ds_write_b64 v1, v[2:3]
	v_mov_b32_e32 v1, 0x221e0
	v_mov_b64_e32 v[2:3], s[72:73]
	ds_write_b64 v1, v[2:3]
